# attention unit: all four start-of-branch tile loads hoisted (pass-1 key tile + gates at unit top; selected tile 0 at pass-2 start; window tile 0 at selected start), on top of v94
# baseline (speedup 1.0000x reference)
.LBB0_1182:
	v_mov_b32_e32 v32, v131
	s_nop 1
	v_permlane32_swap_b32_e32 v131, v32
	v_add_f32_e32 v32, v131, v32
	v_div_scale_f32 v34, s[0:1], v32, v32, 1.0
	v_rcp_f32_e32 v35, v34
	v_cmp_lt_f32_e64 s[12:13], 0, v32
	s_lshl_b32 s48, s58, 1
	v_mov_b32_e32 v131, v177
	v_fma_f32 v36, -v34, v35, 1.0
	v_fmac_f32_e32 v35, v36, v35
	v_div_scale_f32 v36, vcc, 1.0, v32, 1.0
	v_mul_f32_e32 v37, v36, v35
	v_fma_f32 v38, -v34, v37, v36
	v_fmac_f32_e32 v37, v38, v35
	v_fma_f32 v34, -v34, v37, v36
	v_div_fmas_f32 v34, v34, v35, v37
	v_div_fixup_f32 v32, v34, v32, 1.0
	ds_read2st64_b32 v[34:35], v157 offset1:8
	ds_read2st64_b32 v[36:37], v157 offset0:128 offset1:136
	v_cndmask_b32_e64 v32, 0, v32, s[12:13]
	v_readlane_b32 s0, v253, 3
	s_add_i32 s41, s41, s0
	s_add_i32 s40, s40, s0
	s_cmpk_gt_i32 s41, 0x3ff
	v_readlane_b32 s1, v253, 4
	s_waitcnt vmcnt(0)
	v_mov_b32_e32 v33, v251
	v_mul_f32_e32 v32, v33, v32
	s_waitcnt lgkmcnt(1)
	v_pk_fma_f32 v[16:17], v[16:17], v[32:33], v[34:35] op_sel_hi:[1,0,1]
	s_waitcnt lgkmcnt(0)
	v_pk_fma_f32 v[0:1], v[0:1], v[32:33], v[36:37] op_sel_hi:[1,0,1]
	ds_read2st64_b32 v[34:35], v157 offset0:16 offset1:24
	ds_read2st64_b32 v[36:37], v157 offset0:144 offset1:152
	v_cvt_pk_bf16_f32 v0, v0, v1
	v_cvt_pk_bf16_f32 v16, v16, v17
	s_waitcnt lgkmcnt(1)
	v_pk_fma_f32 v[18:19], v[18:19], v[32:33], v[34:35] op_sel_hi:[1,0,1]
	s_waitcnt lgkmcnt(0)
	v_pk_fma_f32 v[2:3], v[2:3], v[32:33], v[36:37] op_sel_hi:[1,0,1]
	ds_read2st64_b32 v[34:35], v157 offset0:32 offset1:40
	ds_read2st64_b32 v[36:37], v157 offset0:160 offset1:168
	v_cvt_pk_bf16_f32 v1, v2, v3
	v_cvt_pk_bf16_f32 v17, v18, v19
	s_waitcnt lgkmcnt(1)
	v_pk_fma_f32 v[20:21], v[20:21], v[32:33], v[34:35] op_sel_hi:[1,0,1]
	s_waitcnt lgkmcnt(0)
	v_pk_fma_f32 v[4:5], v[4:5], v[32:33], v[36:37] op_sel_hi:[1,0,1]
	ds_read2st64_b32 v[34:35], v157 offset0:48 offset1:56
	ds_read2st64_b32 v[36:37], v157 offset0:176 offset1:184
	s_waitcnt lgkmcnt(1)
	v_pk_fma_f32 v[22:23], v[22:23], v[32:33], v[34:35] op_sel_hi:[1,0,1]
	s_waitcnt lgkmcnt(0)
	v_pk_fma_f32 v[6:7], v[6:7], v[32:33], v[36:37] op_sel_hi:[1,0,1]
	ds_read2st64_b32 v[34:35], v157 offset0:64 offset1:72
	ds_read2st64_b32 v[36:37], v157 offset0:192 offset1:200
	s_waitcnt lgkmcnt(1)
	v_pk_fma_f32 v[24:25], v[24:25], v[32:33], v[34:35] op_sel_hi:[1,0,1]
	s_waitcnt lgkmcnt(0)
	v_pk_fma_f32 v[8:9], v[8:9], v[32:33], v[36:37] op_sel_hi:[1,0,1]
	ds_read2st64_b32 v[34:35], v157 offset0:80 offset1:88
	ds_read2st64_b32 v[36:37], v157 offset0:208 offset1:216
	s_waitcnt lgkmcnt(1)
	v_pk_fma_f32 v[26:27], v[26:27], v[32:33], v[34:35] op_sel_hi:[1,0,1]
	s_waitcnt lgkmcnt(0)
	v_pk_fma_f32 v[10:11], v[10:11], v[32:33], v[36:37] op_sel_hi:[1,0,1]
	ds_read2st64_b32 v[34:35], v157 offset0:96 offset1:104
	ds_read2st64_b32 v[36:37], v157 offset0:224 offset1:232
	s_waitcnt lgkmcnt(1)
	v_pk_fma_f32 v[28:29], v[28:29], v[32:33], v[34:35] op_sel_hi:[1,0,1]
	s_waitcnt lgkmcnt(0)
	v_pk_fma_f32 v[12:13], v[12:13], v[32:33], v[36:37] op_sel_hi:[1,0,1]
	ds_read2st64_b32 v[34:35], v157 offset0:112 offset1:120
	ds_read2st64_b32 v[36:37], v157 offset0:240 offset1:248
	s_waitcnt lgkmcnt(1)
	v_pk_fma_f32 v[30:31], v[30:31], v[32:33], v[34:35] op_sel_hi:[1,0,1]
	s_waitcnt lgkmcnt(0)
	v_pk_fma_f32 v[14:15], v[14:15], v[32:33], v[36:37] op_sel_hi:[1,0,1]
	v_lshl_add_u64 v[32:33], v[132:133], 1, s[22:23]
	v_lshl_add_u64 v[32:33], v[32:33], 0, s[48:49]
	v_lshl_add_u64 v[32:33], v[32:33], 0, v[130:131]
	global_store_dwordx2 v[32:33], v[0:1], off offset:64
	v_cvt_pk_bf16_f32 v0, v20, v21
	v_cvt_pk_bf16_f32 v1, v22, v23
	global_store_dwordx2 v[32:33], v[0:1], off offset:16
	v_cvt_pk_bf16_f32 v0, v4, v5
	v_cvt_pk_bf16_f32 v1, v6, v7
	global_store_dwordx2 v[32:33], v[0:1], off offset:80
	v_cvt_pk_bf16_f32 v0, v24, v25
	v_cvt_pk_bf16_f32 v1, v26, v27
	global_store_dwordx2 v[32:33], v[0:1], off offset:32
	v_cvt_pk_bf16_f32 v0, v8, v9
	v_cvt_pk_bf16_f32 v1, v10, v11
	global_store_dwordx2 v[32:33], v[0:1], off offset:96
	v_cvt_pk_bf16_f32 v0, v28, v29
	v_cvt_pk_bf16_f32 v1, v30, v31
	global_store_dwordx2 v[32:33], v[0:1], off offset:48
	v_cvt_pk_bf16_f32 v0, v12, v13
	v_cvt_pk_bf16_f32 v1, v14, v15
	global_store_dwordx2 v[32:33], v[16:17], off
	global_store_dwordx2 v[32:33], v[0:1], off offset:112
	s_barrier
	s_cbranch_scc1 .LBB0_1316
.LBB0_1183:
	s_bfe_u32 s0, s41, 0x50003
	s_ashr_i32 s86, s41, 3
	s_and_b32 s36, s86, 0xffffffe0
	s_and_b32 s1, s41, 0x100
	s_xor_b32 s12, s0, 31
	s_cmp_eq_u32 s1, 0
	s_cselect_b32 s67, s0, s12
	s_lshl_b32 s0, s41, 2
	s_and_b32 s0, s0, 12
	s_or_b32 s33, s67, s36
	s_or_b32 s17, s0, s66
	s_lshl_b32 s0, s41, 11
	v_lshl_add_u32 v1, s33, 6, v158
	s_and_b32 s0, s0, 0x2000
	v_add_u32_e32 v36, s0, v1
	v_ashrrev_i32_e32 v37, 31, v36
	v_lshlrev_b64 v[2:3], 11, v[36:37]
	v_lshl_add_u64 v[2:3], s[18:19], 0, v[2:3]
	s_lshl_b32 s48, s17, 7
	v_lshl_add_u64 v[2:3], v[2:3], 0, s[48:49]
	v_lshl_add_u64 v[2:3], v[2:3], 0, v[176:177]
	global_load_dwordx4 v[100:103], v[2:3], off
	global_load_dwordx4 v[104:107], v[2:3], off offset:32
	global_load_dwordx4 v[108:111], v[2:3], off offset:64
	global_load_dwordx4 v[112:115], v[2:3], off offset:96
	s_and_b32 s100, s41, 7
	s_lshl_b32 s100, s100, 16
	v_readlane_b32 s98, v255, 10
	v_readlane_b32 s99, v255, 11
	s_nop 1
	s_add_u32 s98, s98, s100
	s_addc_u32 s99, s99, 0
	v_lshl_add_u64 v[242:243], v[120:121], 1, s[98:99]
	global_load_dwordx4 v[238:241], v[242:243], off
	v_mov_b64_e32 v[246:247], s[20:21]
	s_movk_i32 s100, 0xc0
	v_mad_i64_i32 v[246:247], s[98:99], v36, s100, v[246:247]
	s_lshl_b32 s100, s17, 2
	s_mov_b32 s101, 0
	v_lshl_add_u64 v[246:247], v[246:247], 0, s[100:101]
	global_load_dword v223, v[246:247], off
	global_load_dword v249, v[246:247], off offset:64
	global_load_dword v251, v[246:247], off offset:128
	s_waitcnt vmcnt(7)
	v_and_b32_e32 v0, 0xffff0000, v100
	v_lshlrev_b32_e32 v2, 16, v100
	v_mul_f32_e32 v0, v0, v0
	v_fmac_f32_e32 v0, v2, v2
	v_lshlrev_b32_e32 v2, 16, v101
	v_fmac_f32_e32 v0, v2, v2
	v_and_b32_e32 v2, 0xffff0000, v101
	v_fmac_f32_e32 v0, v2, v2
	v_lshlrev_b32_e32 v2, 16, v102
	v_fmac_f32_e32 v0, v2, v2
	v_and_b32_e32 v2, 0xffff0000, v102
	v_fmac_f32_e32 v0, v2, v2
	v_lshlrev_b32_e32 v2, 16, v103
	v_fmac_f32_e32 v0, v2, v2
	v_and_b32_e32 v2, 0xffff0000, v103
	v_fmac_f32_e32 v0, v2, v2
	s_waitcnt vmcnt(6)
	v_lshlrev_b32_e32 v2, 16, v104
	v_fmac_f32_e32 v0, v2, v2
	v_and_b32_e32 v2, 0xffff0000, v104
	v_fmac_f32_e32 v0, v2, v2
	v_lshlrev_b32_e32 v2, 16, v105
	v_fmac_f32_e32 v0, v2, v2
	v_and_b32_e32 v2, 0xffff0000, v105
	v_fmac_f32_e32 v0, v2, v2
	v_lshlrev_b32_e32 v2, 16, v106
	v_fmac_f32_e32 v0, v2, v2
	v_and_b32_e32 v2, 0xffff0000, v106
	v_fmac_f32_e32 v0, v2, v2
	v_lshlrev_b32_e32 v2, 16, v107
	v_fmac_f32_e32 v0, v2, v2
	v_and_b32_e32 v2, 0xffff0000, v107
	v_fmac_f32_e32 v0, v2, v2
	s_waitcnt vmcnt(5)
	v_lshlrev_b32_e32 v2, 16, v108
	v_fmac_f32_e32 v0, v2, v2
	v_and_b32_e32 v2, 0xffff0000, v108
	v_fmac_f32_e32 v0, v2, v2
	v_lshlrev_b32_e32 v2, 16, v109
	v_fmac_f32_e32 v0, v2, v2
	v_and_b32_e32 v2, 0xffff0000, v109
	v_fmac_f32_e32 v0, v2, v2
	v_lshlrev_b32_e32 v2, 16, v110
	v_fmac_f32_e32 v0, v2, v2
	v_and_b32_e32 v2, 0xffff0000, v110
	v_fmac_f32_e32 v0, v2, v2
	v_lshlrev_b32_e32 v2, 16, v111
	v_fmac_f32_e32 v0, v2, v2
	v_and_b32_e32 v2, 0xffff0000, v111
	v_fmac_f32_e32 v0, v2, v2
	s_waitcnt vmcnt(4)
	v_lshlrev_b32_e32 v2, 16, v112
	v_fmac_f32_e32 v0, v2, v2
	v_and_b32_e32 v2, 0xffff0000, v112
	v_fmac_f32_e32 v0, v2, v2
	v_lshlrev_b32_e32 v2, 16, v113
	v_fmac_f32_e32 v0, v2, v2
	v_and_b32_e32 v2, 0xffff0000, v113
	v_fmac_f32_e32 v0, v2, v2
	v_lshlrev_b32_e32 v2, 16, v114
	v_fmac_f32_e32 v0, v2, v2
	v_and_b32_e32 v2, 0xffff0000, v114
	v_fmac_f32_e32 v0, v2, v2
	v_lshlrev_b32_e32 v2, 16, v115
	v_fmac_f32_e32 v0, v2, v2
	v_and_b32_e32 v2, 0xffff0000, v115
	v_fmac_f32_e32 v0, v2, v2
	v_mov_b32_e32 v2, v0
	s_nop 1
	v_permlane32_swap_b32_e32 v0, v2
	s_mov_b64 s[0:1], exec
	v_readlane_b32 s12, v255, 16
	v_readlane_b32 s13, v255, 17
	s_and_b64 s[12:13], s[0:1], s[12:13]
	s_mov_b64 exec, s[12:13]
	s_cbranch_execz .LBB0_1186
	s_mov_b64 s[12:13], 0
	v_mov_b32_e32 v3, v201
	v_mov_b32_e32 v4, v200

.LBB0_1201:
	s_andn2_b64 vcc, exec, s[14:15]
	s_waitcnt vmcnt(0)
	v_mov_b32_e32 v74, v223
	ds_write_b128 v163, v[238:241]
	ds_write_b16 v167, v96 offset:9216
	ds_write_b16_d16_hi v167, v96 offset:9352
	ds_write_b16 v167, v97 offset:9488
	ds_write_b16_d16_hi v167, v97 offset:9624
	ds_write_b16 v167, v98 offset:9760
	ds_write_b16_d16_hi v167, v98 offset:9896
	ds_write_b16 v167, v99 offset:10032
	ds_write_b16_d16_hi v167, v99 offset:10168
	v_readlane_b32 s98, v254, 46
	v_readlane_b32 s99, v254, 47
	s_lshl_b32 s100, s88, 20
	s_nop 0
	s_add_u32 s98, s98, s100
	s_addc_u32 s99, s99, 0
	s_add_u32 s100, s98, 0xba00000
	s_addc_u32 s101, s99, 0
	v_lshl_add_u64 v[242:243], v[120:121], 1, s[100:101]
	global_load_dwordx4 v[244:247], v[242:243], off
	s_add_u32 s100, s98, 0xc200000
	s_addc_u32 s101, s99, 0
	v_mov_b32_e32 v242, v72
	v_mov_b32_e32 v243, v177
	v_lshl_add_u64 v[242:243], s[100:101], 0, v[242:243]
	v_lshl_add_u64 v[242:243], v[124:125], 1, v[242:243]
	global_load_dwordx4 v[238:241], v[242:243], off
	s_cbranch_vccnz .LBB0_1203
	v_mov_b32_e32 v73, v177
	v_lshl_add_u64 v[2:3], s[0:1], 0, v[72:73]
	v_add_co_u32_e32 v4, vcc, 0x2000, v38
	v_lshl_add_u64 v[2:3], v[124:125], 1, v[2:3]
	s_nop 0
	v_addc_co_u32_e32 v5, vcc, 0, v39, vcc
	v_add_co_u32_e32 v2, vcc, 0x2000, v2
	s_nop 1
	v_addc_co_u32_e32 v3, vcc, 0, v3, vcc
	global_load_dwordx4 v[64:67], v[4:5], off
	global_load_dwordx4 v[96:99], v[2:3], off

.LBB0_1267:
	s_lshl_b32 s12, s88, 20
	s_add_u32 s16, s46, s12
	s_addc_u32 s17, s47, 0
	v_lshl_add_u64 v[74:75], v[120:121], 1, s[16:17]
	v_readlane_b32 s34, v253, 29
	v_readlane_b32 s35, v253, 30
	s_add_u32 s14, s37, s12
	s_addc_u32 s15, s65, 0
	v_cndmask_b32_e64 v0, 0, 1, s[34:35]
	v_cmp_ne_u32_e64 s[12:13], 1, v0
	s_andn2_b64 vcc, exec, s[34:35]
	s_cbranch_vccnz .LBB0_1269
	v_mov_b32_e32 v73, v177
	v_lshl_add_u64 v[0:1], s[14:15], 0, v[72:73]
	v_lshl_add_u64 v[0:1], v[124:125], 1, v[0:1]
.LBB0_1269:
	s_xor_b64 s[0:1], s[0:1], -1
	s_andn2_b64 vcc, exec, s[0:1]
	s_waitcnt vmcnt(0)
	ds_write_b128 v163, v[244:247]
	ds_write_b16 v167, v238 offset:9216
	ds_write_b16_d16_hi v167, v238 offset:9352
	ds_write_b16 v167, v239 offset:9488
	ds_write_b16_d16_hi v167, v239 offset:9624
	ds_write_b16 v167, v240 offset:9760
	ds_write_b16_d16_hi v167, v240 offset:9896
	ds_write_b16 v167, v241 offset:10032
	ds_write_b16_d16_hi v167, v241 offset:10168
	v_readlane_b32 s98, v254, 46
	v_readlane_b32 s99, v254, 47
	s_lshl_b32 s100, s88, 20
	s_add_i32 s101, s33, -8
	s_max_i32 s101, s101, 0
	s_lshl_b32 s101, s101, 13
	s_add_u32 s100, s100, s101
	s_add_u32 s98, s98, s100
	s_addc_u32 s99, s99, 0
	s_add_u32 s98, s98, 0xca00000
	s_addc_u32 s99, s99, 0
	v_lshl_add_u64 v[242:243], v[120:121], 1, s[98:99]
	global_load_dwordx4 v[244:247], v[242:243], off
	v_readlane_b32 s98, v255, 7
	v_readlane_b32 s99, v255, 9
	s_nop 1
	s_add_u32 s98, s98, s100
	s_addc_u32 s99, s99, 0
	v_mov_b32_e32 v242, v72
	v_mov_b32_e32 v243, v177
	v_lshl_add_u64 v[242:243], s[98:99], 0, v[242:243]
	v_lshl_add_u64 v[242:243], v[124:125], 1, v[242:243]
	global_load_dwordx4 v[238:241], v[242:243], off
	s_cbranch_vccnz .LBB0_1271
	s_mov_b32 s55, s49
	s_lshl_b64 s[0:1], s[54:55], 13
	s_add_u32 s34, s14, s0
	s_addc_u32 s35, s15, s1
	s_add_u32 s0, s16, s0
	v_mov_b32_e32 v73, v177
	s_addc_u32 s1, s17, s1
	v_lshl_add_u64 v[0:1], s[34:35], 0, v[72:73]
	v_lshl_add_u64 v[2:3], v[120:121], 1, s[0:1]
	v_lshl_add_u64 v[0:1], v[124:125], 1, v[0:1]
	global_load_dwordx4 v[68:71], v[2:3], off
	global_load_dwordx4 v[96:99], v[0:1], off

.LBB0_1298:
	v_mov_b32_e32 v32, v73
	s_nop 1
	v_permlane32_swap_b32_e32 v73, v32
	v_add_f32_e32 v32, v73, v32
	v_div_scale_f32 v34, s[16:17], v32, v32, 1.0
	v_rcp_f32_e32 v35, v34
	v_cmp_lt_f32_e64 s[14:15], 0, v32
	s_lshl_b32 s0, s88, 19
	v_readlane_b32 s2, v255, 7
	v_fma_f32 v36, -v34, v35, 1.0
	v_fmac_f32_e32 v35, v36, v35
	v_div_scale_f32 v36, vcc, 1.0, v32, 1.0
	v_mul_f32_e32 v37, v36, v35
	v_fma_f32 v38, -v34, v37, v36
	v_fmac_f32_e32 v37, v38, v35
	v_fma_f32 v34, -v34, v37, v36
	v_div_fmas_f32 v34, v34, v35, v37
	v_div_fixup_f32 v32, v34, v32, 1.0
	ds_read2st64_b32 v[34:35], v157 offset0:128 offset1:136
	v_cndmask_b32_e64 v32, 0, v32, s[14:15]
	s_lshl_b32 s14, s0, 1
	s_add_u32 s0, s30, s14
	s_addc_u32 s1, s3, 0
	s_add_u32 s16, s2, s14
	v_readlane_b32 s2, v255, 9
	s_addc_u32 s17, s2, 0
	s_add_i32 s14, s33, -8
	s_cmp_gt_i32 s33, 7
	s_cselect_b32 s14, s14, 0
	s_ashr_i32 s15, s14, 31
	s_lshl_b64 s[34:35], s[14:15], 13
	s_add_u32 s34, s0, s34
	s_addc_u32 s35, s1, s35
	s_and_b64 vcc, exec, s[12:13]
	s_waitcnt vmcnt(0)
	v_mov_b32_e32 v33, v249
	v_mul_f32_e32 v36, v33, v32
	s_waitcnt lgkmcnt(0)
	v_fma_f32 v0, v0, v36, v34
	v_fmac_f32_e32 v35, v1, v36
	ds_write2st64_b32 v157, v0, v35 offset0:128 offset1:136
	ds_read2st64_b32 v[0:1], v157 offset0:16 offset1:24
	ds_read2st64_b32 v[32:33], v157 offset1:8
	s_waitcnt lgkmcnt(1)
	v_fma_f32 v0, v18, v36, v0
	v_fmac_f32_e32 v1, v19, v36
	ds_write2st64_b32 v157, v0, v1 offset0:16 offset1:24
	ds_read2st64_b32 v[0:1], v157 offset0:32 offset1:40
	s_waitcnt lgkmcnt(2)
	v_fma_f32 v16, v16, v36, v32
	v_fmac_f32_e32 v33, v17, v36
	ds_write2st64_b32 v157, v16, v33 offset1:8
	ds_read2st64_b32 v[16:17], v157 offset0:144 offset1:152
	s_waitcnt lgkmcnt(2)
	v_fma_f32 v0, v20, v36, v0
	v_fmac_f32_e32 v1, v21, v36
	ds_write2st64_b32 v157, v0, v1 offset0:32 offset1:40
	ds_read2st64_b32 v[0:1], v157 offset0:48 offset1:56
	s_waitcnt lgkmcnt(2)
	v_fma_f32 v2, v2, v36, v16
	v_fmac_f32_e32 v17, v3, v36
	ds_write2st64_b32 v157, v2, v17 offset0:144 offset1:152
	ds_read2st64_b32 v[2:3], v157 offset0:160 offset1:168
	s_waitcnt lgkmcnt(2)
	v_fma_f32 v0, v22, v36, v0
	v_fmac_f32_e32 v1, v23, v36
	ds_write2st64_b32 v157, v0, v1 offset0:48 offset1:56
	ds_read2st64_b32 v[0:1], v157 offset0:64 offset1:72
	s_waitcnt lgkmcnt(2)
	v_fma_f32 v2, v4, v36, v2
	v_fmac_f32_e32 v3, v5, v36
	ds_write2st64_b32 v157, v2, v3 offset0:160 offset1:168
	ds_read2st64_b32 v[2:3], v157 offset0:176 offset1:184
	s_waitcnt lgkmcnt(2)
	v_fma_f32 v0, v24, v36, v0
	v_fmac_f32_e32 v1, v25, v36
	ds_write2st64_b32 v157, v0, v1 offset0:64 offset1:72
	ds_read2st64_b32 v[0:1], v157 offset0:80 offset1:88
	s_waitcnt lgkmcnt(2)
	v_fma_f32 v2, v6, v36, v2
	v_fmac_f32_e32 v3, v7, v36
	ds_write2st64_b32 v157, v2, v3 offset0:176 offset1:184
	ds_read2st64_b32 v[2:3], v157 offset0:192 offset1:200
	s_waitcnt lgkmcnt(2)
	v_fma_f32 v0, v26, v36, v0
	v_fmac_f32_e32 v1, v27, v36
	ds_write2st64_b32 v157, v0, v1 offset0:80 offset1:88
	ds_read2st64_b32 v[0:1], v157 offset0:96 offset1:104
	s_waitcnt lgkmcnt(2)
	v_fma_f32 v2, v8, v36, v2
	v_fmac_f32_e32 v3, v9, v36
	ds_write2st64_b32 v157, v2, v3 offset0:192 offset1:200
	ds_read2st64_b32 v[2:3], v157 offset0:208 offset1:216
	s_waitcnt lgkmcnt(2)
	v_fma_f32 v0, v28, v36, v0
	v_fmac_f32_e32 v1, v29, v36
	ds_write2st64_b32 v157, v0, v1 offset0:96 offset1:104
	ds_read2st64_b32 v[0:1], v157 offset0:112 offset1:120
	s_waitcnt lgkmcnt(2)
	v_fma_f32 v2, v10, v36, v2
	v_fmac_f32_e32 v3, v11, v36
	ds_write2st64_b32 v157, v2, v3 offset0:208 offset1:216
	ds_read2st64_b32 v[2:3], v157 offset0:224 offset1:232
	s_waitcnt lgkmcnt(2)
	v_fma_f32 v0, v30, v36, v0
	v_fmac_f32_e32 v1, v31, v36
	ds_write2st64_b32 v157, v0, v1 offset0:112 offset1:120
	v_lshl_add_u64 v[0:1], v[120:121], 1, s[34:35]
	s_waitcnt lgkmcnt(1)
	v_fma_f32 v2, v12, v36, v2
	v_fmac_f32_e32 v3, v13, v36
	ds_write2st64_b32 v157, v2, v3 offset0:224 offset1:232
	ds_read2st64_b32 v[2:3], v157 offset0:240 offset1:248
	s_waitcnt lgkmcnt(0)
	v_fma_f32 v2, v14, v36, v2
	v_fmac_f32_e32 v3, v15, v36
	ds_write2st64_b32 v157, v2, v3 offset0:240 offset1:248
	s_cbranch_vccnz .LBB0_1300
	s_lshl_b64 s[34:35], s[14:15], 12
	s_lshl_b64 s[34:35], s[34:35], 1
	s_add_u32 s34, s16, s34
	s_addc_u32 s35, s17, s35
	v_mov_b32_e32 v73, v177
	v_lshl_add_u64 v[0:1], s[34:35], 0, v[72:73]
	v_lshl_add_u64 v[0:1], v[124:125], 1, v[0:1]
.LBB0_1300:
	s_cmp_ge_i32 s14, s33
	s_waitcnt vmcnt(0)
	ds_write_b128 v163, v[244:247]
	ds_write_b16 v167, v238 offset:9216
	ds_write_b16_d16_hi v167, v238 offset:9352
	ds_write_b16 v167, v239 offset:9488
	ds_write_b16_d16_hi v167, v239 offset:9624
	ds_write_b16 v167, v240 offset:9760
	ds_write_b16_d16_hi v167, v240 offset:9896
	ds_write_b16 v167, v241 offset:10032
	ds_write_b16_d16_hi v167, v241 offset:10168
	s_cbranch_scc1 .LBB0_1303
	s_add_i32 s54, s14, 1
	s_ashr_i32 s55, s54, 31
	s_lshl_b64 s[34:35], s[54:55], 13
	s_add_u32 s34, s0, s34
	s_addc_u32 s35, s1, s35
	v_lshl_add_u64 v[0:1], v[120:121], 1, s[34:35]
	global_load_dwordx4 v[116:119], v[0:1], off
	s_and_b64 vcc, exec, s[12:13]
	s_cbranch_vccnz .LBB0_1303
	s_lshl_b64 s[34:35], s[54:55], 12
	s_lshl_b64 s[34:35], s[34:35], 1
	s_add_u32 s34, s16, s34
	s_addc_u32 s35, s17, s35
	v_mov_b32_e32 v73, v177
	v_lshl_add_u64 v[0:1], s[34:35], 0, v[72:73]
	v_lshl_add_u64 v[0:1], v[124:125], 1, v[0:1]
	global_load_dwordx4 v[96:99], v[0:1], off
